# attention units re-dealt 35/33 block pairs between early and late workgroups (tuned with a repeat-region probe) + P4 6/10 split + P3 carry move
# speedup vs baseline: 1.0044x; 1.0044x over previous
;   __device__ __forceinline__ bool next(int i,AttnUnit&u)const{
;     if(G==256){ if(i>=4)return false; const int s=vcu&3; u.bh=vcu>>2; u.qb=(i==0)?s:(i==1)?7-s:(i==2)?8+s:15-s; return true; }
;     const int L=i*G+vcu; if(L>=BATCH*NHEAD*NQB)return false; u.bh=L/NQB; u.qb=NQB-1-(L%NQB); return true; }
.LBB0_549:
	s_andn2_b64 vcc, exec, s[6:7]
	s_cbranch_vccnz .LBB0_558
	s_bfe_u32 s3, s22, 0x10004
	s_and_b32 s10, s22, 3
	s_lshl_b32 s3, s3, 2
	s_or_b32 s3, s3, s10
	s_mov_b32 s10, 0x8a5a6f
	s_cmp_eq_u32 s3, 1
	s_cselect_b32 s10, 0x8e4aae, s10
	s_cmp_eq_u32 s3, 2
	s_cselect_b32 s10, 0x20ca7a2d, s10
	s_cmp_eq_u32 s3, 3
	s_cselect_b32 s10, 0x30866aec, s10
	s_cmp_eq_u32 s3, 4
	s_cselect_b32 s10, 0x21baf, s10
	s_cmp_eq_u32 s3, 5
	s_cselect_b32 s10, 0x26aed, s10
	s_cmp_eq_u32 s3, 6
	s_cselect_b32 s10, 0x8e4aac, s10
	s_cmp_eq_u32 s3, 7
	s_cselect_b32 s10, 0x967a29, s10
	s_mul_i32 s3, s70, 6
	s_min_u32 s3, s3, 31
	s_lshr_b32 s10, s10, s3
	s_bitcmp1_b32 s10, 5
	s_cbranch_scc0 .Lau_done
	s_and_b32 s72, s10, 15
	s_lshr_b32 s3, s10, 2
	s_and_b32 s3, s3, 4
	s_xor_b32 s71, s60, s3
	s_mov_b64 s[4:5], -1
	s_branch .LBB0_559
